# scan role 3: kk normalisation via pairwise sum tree and min(rsq(ss),1e12); VN tiles of waves 6,7 moved to the light LoRA waves 2,3
# baseline (speedup 1.0000x reference)
; __device__ __forceinline__ uint2 pack4(f32x4 v) { uint2 u; u.x = cvt_pk_bf16(v[0], v[1]); u.y = cvt_pk_bf16(v[2], v[3]); return u; }
; #define MFMA16(a, b, c) __builtin_amdgcn_mfma_f32_16x16x32_bf16(a, b, c, 0, 0, 0)
; __device__ __forceinline__ void scan_phase(PREF p, char* smem, const int wid_u) {
;     ...
;     for (int c = 0; c < nch; ++c) {
;       {
;         const int mat = wave >> 1, mts = wave & 1;
;         const bf16_t* As = (mat & 1) ? Kt : Bt;
;         const bf16_t* Bs = (mat & 2) ? Rt : At;
;         f32x4 acc[2] = {};
; #pragma unroll
;         for (int ks = 0; ks < 2; ++ks) {
;           const bf16x8 a = ldfrag(As, 72, mts * 16, ks * 32, fr, fq);
; #pragma unroll
;           for (int nt = 0; nt < 2; ++nt) acc[nt] = MFMA16(a, ldfrag(Bs, 72, nt * 16, ks * 32, fr, fq), acc[nt]);
;         }
; #pragma unroll
;         for (int nt = 0; nt < 2; ++nt) {
;           const int tcol = nt * 16 + fr;
;           f32x4 v = acc[nt];
; #pragma unroll
;           for (int jj = 0; jj < 4; ++jj) {
;             const int srow = mts * 16 + fq * 4 + jj;
;             const bool keep = (mat & 2) ? (srow <= tcol) : (srow < tcol);
;             v[jj] = keep ? v[jj] : 0.f;
;           }
;           if (mat == 0) {
; #pragma unroll
;             for (int jj = 0; jj < 4; ++jj) Nab[(mts * 16 + fq * 4 + jj) * 32 + tcol] = v[jj];
;           } else {
;             bf16_t* dst = mat == 1 ? NakT : mat == 2 ? NbrT : NkrT;
;             *(uint2*)(dst + tcol * 40 + mts * 16 + fq * 4) = pack4(v);
;           }
;         }
;       }
;       lds_barrier();
;       if (wave == 4) {
;         const int irow = lane >> 1, hb = lane & 1, blk = lane >> 5, il = irow & 15;
;         float x[8];
; #pragma unroll
;         for (int i = 0; i < 8; ++i) x[i] = (hb * 8 + i == il) ? 1.f : 0.f;
;         const float* nb = Nab + (blk * 16) * 32 + blk * 16 + hb * 8;
;         solve16<0>(x, nb);
; #pragma unroll
;         for (int i = 0; i < 8; ++i) TT[(blk * 16 + hb * 8 + i) * 40 + blk * 16 + il] = (bf16_t)(cvt_pk_bf16(x[i], 0.f) & 0xffff);
;         if (blk == 0) *(uint4*)(T11b + il * 40 + hb * 8) = pack8(x);
.LBB0_537:
	s_lshr_b32 s44, s92, 5
	s_mul_i32 s18, s26, 0x6000000
	s_add_u32 s18, s48, s18
	s_addc_u32 s19, s49, 0
	s_add_u32 s64, s18, 0xee90000
	s_addc_u32 s65, s19, 0
	s_cmp_eq_u32 s20, 0
	s_mov_b32 s18, 0xe400
	v_lshlrev_b32_e32 v80, 2, v79
	s_cselect_b32 s18, s18, 0xf600
	v_or_b32_e32 v48, s84, v80
	s_add_i32 s20, s18, 0
	s_and_b32 s18, s90, 4
	s_add_i32 s28, 0, 0xc000
	s_add_i32 s29, 0, 0xd200
	v_cmp_lt_u32_e32 vcc, v48, v77
	s_cmp_eq_u32 s18, 0
	v_mul_u32_u24_e32 v128, 0x90, v90
	v_cndmask_b32_e64 v49, 0, 1, vcc
	v_cmp_le_u32_e32 vcc, v48, v77
	v_mul_u32_u24_e32 v69, 40, v77
	v_add_u32_e32 v138, s27, v55
	v_cndmask_b32_e64 v50, 0, 1, vcc
	s_cselect_b64 vcc, -1, 0
	v_cndmask_b32_e32 v49, v50, v49, vcc
	s_and_b64 s[18:19], vcc, exec
	v_lshlrev_b32_e32 v50, 1, v78
	s_cselect_b32 s18, s28, s29
	v_add3_u32 v129, s20, v128, v50
	s_add_i32 s20, 0, 0x2a00
	s_add_i32 s28, 0, 0x2000
	v_add_u32_e32 v51, s18, v50
	s_and_b64 s[18:19], s[22:23], exec
	s_cselect_b32 s18, s28, s20
	s_add_i32 s19, 0, 0x1000
	s_cmp_eq_u32 s25, 1
	s_cselect_b32 s18, s19, s18
	s_lshl_b32 s19, s84, 1
	s_add_i32 s18, s18, s19
	v_add_u32_e32 v52, s18, v78
	s_add_i32 s18, 0, 0x13000
	v_add_u32_e32 v131, s18, v50
	s_add_i32 s18, 0, 0x25100
	v_add_u32_e32 v53, s18, v55
	s_add_i32 s18, 0, 0x1f100
	v_add_u32_e32 v56, s18, v55
	s_add_i32 s18, 0, 0x10800
	s_add_i32 s20, 0, 0x1d100
	s_add_i32 s34, 0, 0x21100
	s_add_i32 s35, 0, 0x14400
	s_add_i32 s36, s19, 0
	v_add_u32_e32 v57, s18, v50
	s_add_i32 s18, 0, 0x11c00
	s_and_b32 s28, s90, -2
	s_cmp_eq_u32 s28, 2
	s_cselect_b64 s[28:29], -1, 0
	s_cmp_gt_i32 s90, 5
	s_cselect_b64 s[30:31], -1, 0
	s_or_b64 s[66:67], s[30:31], s[28:29]
	s_cmp_lt_u32 s90, 4
	s_cselect_b32 s28, -2, -4
	v_add3_u32 v139, s20, v55, v54
	s_add_i32 s20, 0, 0x27500
	v_add_u32_e32 v141, s20, v55
	s_add_i32 s20, 0, 0x27900
	v_add_u32_e32 v142, s20, v55
	s_add_i32 s20, 0, 0x27400
	v_add_u32_e32 v130, 0, v50
	s_add_i32 s28, s28, s90
	v_add_u32_e32 v143, s20, v55
	s_add_i32 s20, 0, 0x27200
	v_lshl_add_u32 v134, v69, 1, v130
	v_lshl_or_b32 v69, s28, 4, v77
	s_add_i32 s28, 0, 0x27300
	v_add_u32_e32 v144, s20, v55
	s_lshl_b32 s20, s89, 1
	s_add_u32 s27, s64, s20
	v_add_u32_e32 v137, s28, v55
	s_addc_u32 s28, s65, 0
	s_lshl_b32 s68, s25, 4
	v_add_u32_e32 v59, s21, v55
	v_lshl_add_u32 v68, v77, 7, 0
	v_mul_i32_i24_e32 v70, 0xffffffd0, v77
	v_add3_u32 v140, s34, v55, v54
	v_lshlrev_b32_e32 v55, 2, v77
	s_ashr_i32 s69, s68, 31
	v_add3_u32 v133, v68, v70, v50
	v_add_u32_e32 v70, s21, v55
	s_lshl_b64 s[20:21], s[68:69], 1
	s_add_u32 s20, s27, s20
	s_addc_u32 s21, s28, s21
	v_mov_b32_e32 v79, 0
	v_lshl_add_u64 v[82:83], s[20:21], 0, v[78:79]
	v_cmp_eq_u32_e64 s[20:21], 0, v89
	s_and_b64 s[70:71], s[20:21], s[22:23]
	s_lshl_b32 s20, s24, 3
	s_add_u32 s20, s48, s20
	s_addc_u32 s21, s49, 0
	s_lshl_b32 s22, s26, 2
	s_add_u32 s20, s20, s22
	v_mul_u32_u24_e32 v71, 40, v90
	s_movk_i32 s37, 0x50
	s_addc_u32 s21, s21, 0
	v_lshl_add_u32 v145, v71, 1, v130
	v_or_b32_e32 v71, s68, v77
	s_add_u32 s72, s20, 0x2890000
	v_mul_lo_u32 v84, v71, s37
	v_lshl_or_b32 v85, s40, 5, v77
	s_addc_u32 s73, s21, 0
	s_add_i32 s45, s92, -1
	v_add_u32_e32 v147, v130, v84
	v_add3_u32 v148, s35, v50, v84
	v_add3_u32 v149, s36, v84, v78
	v_add_u32_e32 v152, v131, v84
	v_mul_u32_u24_e32 v84, 40, v85
	v_or_b32_e32 v92, 2, v48
	v_add_u32_e32 v58, s18, v50
	s_add_u32 s74, s48, 0x3be90000
	v_lshlrev_b32_e32 v84, 1, v84
	v_cmp_lt_u32_e64 s[26:27], v92, v77
	s_addc_u32 s75, s49, 0
	s_add_i32 s22, 0, 0x16800
	v_add_u32_e32 v153, v57, v84
	v_add_u32_e32 v155, v58, v84
	v_cndmask_b32_e64 v84, 0, 1, s[26:27]
	v_cmp_le_u32_e64 s[26:27], v92, v77
	v_lshl_add_u32 v150, v85, 2, s22
	v_or_b32_e32 v86, 16, v85
	v_mul_u32_u24_e32 v157, 0x90, v85
	v_cndmask_b32_e64 v85, 0, 1, s[26:27]
	v_cndmask_b32_e32 v84, v85, v84, vcc
	v_or_b32_e32 v93, 3, v48
	v_and_b32_e32 v84, 1, v84
	v_cmp_lt_u32_e64 s[28:29], v93, v77
	v_mul_u32_u24_e32 v87, 40, v86
	v_cmp_eq_u32_e64 s[26:27], 1, v84
	v_cndmask_b32_e64 v84, 0, 1, s[28:29]
	v_cmp_le_u32_e64 s[28:29], v93, v77
	v_lshlrev_b32_e32 v87, 1, v87
	v_add_u32_e32 v156, v58, v87
	v_cndmask_b32_e64 v85, 0, 1, s[28:29]
	v_or_b32_e32 v58, 16, v77
	v_cndmask_b32_e32 v84, v85, v84, vcc
	v_and_b32_e32 v84, 1, v84
	v_cmp_lt_u32_e64 s[30:31], v48, v58
	v_add_u32_e32 v154, v57, v87
	s_lshl_b32 s20, s25, 5
	v_mul_u32_u24_e32 v57, 0x48, v90
	v_and_b32_e32 v49, 1, v49
	v_cmp_eq_u32_e64 s[28:29], 1, v84
	v_cndmask_b32_e64 v84, 0, 1, s[30:31]
	v_cmp_le_u32_e64 s[30:31], v48, v58
	s_movk_i32 s41, 0x90
	v_lshl_add_u32 v151, v86, 2, s22
	s_add_i32 s20, s20, 0
	v_lshlrev_b32_e32 v57, 1, v57
	v_lshl_add_u32 v164, v88, 2, s22
	v_cmp_eq_u32_e64 s[22:23], 1, v49
	v_or_b32_e32 v49, 1, v48
	v_cndmask_b32_e64 v85, 0, 1, s[30:31]
	v_mad_u32_u24 v60, v113, s37, 0
	v_mul_lo_u32 v136, v69, s37
	v_add3_u32 v161, s20, v57, v78
	v_mul_lo_u32 v57, v71, s41
	v_cndmask_b32_e32 v71, v48, v49, vcc
	v_cndmask_b32_e32 v84, v85, v84, vcc
	v_cmp_lt_u32_e64 s[36:37], v92, v58
	v_cmp_gt_u32_e64 s[24:25], v77, v71
	v_and_b32_e32 v84, 1, v84
	v_cmp_gt_u32_e64 s[34:35], v58, v71
	v_cndmask_b32_e64 v71, 0, 1, s[36:37]
	v_cmp_le_u32_e64 s[36:37], v92, v58
	v_cmp_eq_u32_e64 s[30:31], 1, v84
	v_cmp_lt_u32_e64 s[38:39], v93, v58
	v_cndmask_b32_e64 v84, 0, 1, s[36:37]
	v_cndmask_b32_e32 v71, v84, v71, vcc
	v_and_b32_e32 v71, 1, v71
	v_cmp_eq_u32_e64 s[36:37], 1, v71
	v_cndmask_b32_e64 v71, 0, 1, s[38:39]
	v_cmp_le_u32_e64 s[38:39], v93, v58
	v_lshrrev_b32_e32 v62, 1, v75
	v_lshlrev_b32_e32 v64, 3, v75
	v_cndmask_b32_e64 v58, 0, 1, s[38:39]
	v_cndmask_b32_e32 v58, v58, v71, vcc
	v_and_b32_e32 v58, 1, v58
	v_lshrrev_b32_e32 v63, 5, v88
	v_cmp_eq_u32_e64 s[38:39], 1, v58
	v_and_b32_e32 v58, 15, v62
	v_and_b32_e32 v62, 8, v64
	v_lshl_add_u32 v65, v63, 11, 0
	v_lshlrev_b32_e32 v66, 6, v63
	v_lshlrev_b32_e32 v64, 2, v62
	v_mul_i32_i24_e32 v67, 0xfffff820, v63
	v_add3_u32 v166, v65, v66, v64
	v_lshlrev_b32_e32 v64, 1, v58
	v_add3_u32 v64, v65, v67, v64
	v_mul_u32_u24_e32 v65, 0x50, v58
	v_lshlrev_b32_e32 v66, 1, v62
	v_add3_u32 v167, 0, v65, v66
	v_or_b32_e32 v65, 1, v62
	v_cmp_eq_u32_e32 vcc, v62, v58
	v_or_b32_e32 v66, 2, v62
	v_mul_u32_u24_e32 v159, 0x90, v86
	v_cndmask_b32_e64 v84, 0, 1.0, vcc
	v_cmp_eq_u32_e32 vcc, v58, v65
	v_or_b32_e32 v65, 3, v62
	s_add_i32 s47, 0, 0x16900
	v_cndmask_b32_e64 v85, 0, 1.0, vcc
	v_cmp_eq_u32_e32 vcc, v65, v58
	v_or_b32_e32 v65, 5, v62
	v_lshlrev_b32_e32 v61, 3, v89
	v_cndmask_b32_e64 v87, 0, 1.0, vcc
	v_cmp_eq_u32_e32 vcc, v66, v58
	v_or_b32_e32 v66, 4, v62
	s_cmp_gt_i32 s90, 4
	v_cndmask_b32_e64 v86, 0, 1.0, vcc
	v_cmp_eq_u32_e32 vcc, v65, v58
	v_or_b32_e32 v65, 7, v62
	s_waitcnt lgkmcnt(0)
	s_barrier
; __device__ __forceinline__ void scan_phase(PREF p, char* smem, const int wid_u) {
;     ...
;     uint4* Btab0 = (uint4*)(p.ws + OFF_BTAB);
;     const unsigned bti = (unsigned)(item * 1024 + (role & 1) * 512 + lane);
;     float bias[4] = {0.f, 0.f, 0.f, 0.f};
;     if (role < 2) {
;       const float* lsrc = sel(role != 0, p.a2, p.w2) + (size_t)d * 64 * 512 + h * 64;
;       if (th == 0) {
; #pragma unroll
;         for (int nt = 0; nt < 4; ++nt)
; #pragma unroll
;           for (int ks = 0; ks < 2; ++ks) {
;             float o[8];
; #pragma unroll
;             for (int q = 0; q < 8; ++q) o[q] = lsrc[(size_t)(ks * 32 + fq * 8 + q) * 512 + nt * 16 + fr];
;             Btab0[bti + (unsigned)((nt * 2 + ks) * 64)] = pack8(o);
;           }
;       }
; #pragma unroll
;       for (int nt = 0; nt < 4; ++nt) bias[nt] = sel(role != 0, p.a0, p.w0)[d * 512 + h * 64 + nt * 16 + fr];
;     }
;     const int colA = (role == 2 ? 512 : 1024) + h * 64 + cq * 16;
;     const int colB = 1536 + h * 64 + cq * 16;
;     const int alo = (role == 0 ? d * 64 : 128 + d * 64) + fq * 8;
;     Raw16 ra, rb;
;     {
;       const int j = th * 16 + tl, t = d ? T - 1 - j : j, row = r0seq + t;
;       if (role >= 2) load_raw16(ra, z, row, t, T, colA);
;       if (role == 3) load_raw16(rb, z, row, t, T, colB);
;       if (role < 2) {
;         const int j2 = th * 16 + fr, t2 = d ? T - 1 - j2 : j2;
;         const bf16_t* ap = P_ALORA + (unsigned)((r0seq + t2) * 256 + alo);
;         ra.c0 = *(const uint4*)ap; ra.c1 = *(const uint4*)(ap + 32);
;       }
;     }
;     f32x4 Sa = {0.f, 0.f, 0.f, 0.f}, Sb = Sa;
;     uint2 y_def = make_uint2(0u, 0u);
;     float sb_def = 0.f;
;     const int mt = wave >> 1, hn = wave & 1, nt0 = 2 * hn, nt1 = 2 * hn + 1;
;     asm volatile("s_waitcnt vmcnt(0)" ::: "memory");
;     __syncthreads();
;     {
;       {
;         const int j = th * 16 + tl;
;         float v16[16];
;         if (role < 2) {
;           f32x4 acc[4] = {};
;           unsigned bti_ = bti;
;           asm volatile("" : "+v"(bti_));
; #pragma unroll
;           for (int ks = 0; ks < 2; ++ks) {
;             const uint4 au = ks == 0 ? ra.c0 : ra.c1;
;             const bf16x8 a = *reinterpret_cast<const bf16x8*>(&au);
; #pragma unroll
	v_cndmask_b32_e64 v89, 0, 1.0, vcc
	v_cmp_eq_u32_e32 vcc, v66, v58
	v_cmp_gt_u32_e64 s[18:19], 32, v88
	v_add3_u32 v158, s20, v157, v78
	v_add3_u32 v160, s20, v159, v78
	v_add3_u32 v162, s47, v57, v50
	v_or_b32_e32 v50, s68, v80
	s_cselect_b64 s[20:21], -1, 0
	v_lshl_or_b32 v63, v63, 4, v62
	v_cndmask_b32_e64 v88, 0, 1.0, vcc
	v_or_b32_e32 v62, 6, v62
	v_cmp_eq_u32_e32 vcc, v65, v58
	s_lshl_b32 s40, s40, 6
	v_lshl_add_u32 v132, v78, 2, v68
	v_sub_u32_e32 v68, 0, v78
	v_add_u32_e32 v69, 0, v136
	v_mul_u32_u24_e32 v57, 0x90, v77
	v_mul_u32_u24_e32 v165, 0x50, v77
	v_add_u32_e32 v55, 0, v55
	v_lshlrev_b32_e32 v94, 7, v48
	v_lshlrev_b32_e32 v95, 7, v49
	v_lshlrev_b32_e32 v96, 7, v92
	v_lshlrev_b32_e32 v97, 7, v93
	v_cndmask_b32_e64 v91, 0, 1.0, vcc
	v_cmp_eq_u32_e32 vcc, v62, v58
	v_mul_u32_u24_e32 v58, 0x50, v63
	v_lshlrev_b32_e32 v48, 8, v48
	v_lshlrev_b32_e32 v49, 8, v49
	v_lshlrev_b32_e32 v62, 8, v92
	v_lshlrev_b32_e32 v63, 8, v93
	s_add_i32 s47, s47, s40
	v_lshlrev_b32_e32 v65, 1, v77
	v_mul_lo_u32 v50, v50, s41
	s_movk_i32 s76, 0xec00
	v_sub_u32_e32 v135, v133, v78
	v_add_u32_e32 v163, 0xffffff00, v115
	v_cndmask_b32_e64 v90, 0, 1.0, vcc
	s_lshl_b32 s46, s90, 12
	v_add3_u32 v168, s47, v65, v50
	s_sub_i32 s47, 0, s84
	v_sub_u32_e32 v169, s92, v77
	v_sub_u32_e32 v170, s92, v113
	s_sub_i32 s87, 0, s44
	v_add_u32_e32 v171, v51, v57
	v_add_u32_e32 v172, v60, v61
	v_add_u32_e32 v173, v69, v78
	v_add_u32_e32 v174, v64, v58
	v_add_u32_e32 v175, v133, v68
	v_mov_b32_e32 v176, 0x260
	v_add_u32_e32 v177, v53, v54
	v_add_u32_e32 v178, v56, v54
	s_movk_i32 s88, 0xa00
	s_mov_b32 s77, -1
	s_mov_b64 s[78:79], 0x1400
	v_add_u32_e32 v179, v59, v54
	v_add_u32_e32 v180, v52, v165
	v_add_u32_e32 v181, v55, v94
	v_add_u32_e32 v182, v55, v95
	v_add_u32_e32 v183, v55, v96
	v_add_u32_e32 v184, v55, v97
	v_add_u32_e32 v185, v70, v48
	v_add_u32_e32 v186, v70, v49
	v_add_u32_e32 v187, v70, v62
	v_add_u32_e32 v188, v70, v63
	s_mov_b32 s93, s84
	v_mov_b32_e32 v48, v79
	v_mov_b32_e32 v49, v79
	v_mov_b32_e32 v50, v79
	v_mov_b32_e32 v51, v79
	v_mov_b32_e32 v52, v79
	v_mov_b32_e32 v53, v79
	v_mov_b32_e32 v54, v79
	v_mov_b32_e32 v55, v79
	v_mov_b32_e32 v92, v79
	v_mov_b32_e32 v93, v79
	s_load_dwordx2 s[100:101], s[0:1], 0x110
	s_lshr_b32 s98, s33, 4
	s_lshl_b32 s98, s98, 8
	s_and_b32 s99, s33, 15
	s_lshl_b32 s99, s99, 2
	s_add_u32 s98, s98, s99
	s_add_u32 s98, s98, 0x3ee90440
	s_waitcnt lgkmcnt(0)
	s_add_u32 s100, s100, s98
	s_addc_u32 s101, s101, 0
	s_cmp_gt_u32 s90, 3
	s_cbranch_scc1 .Lbt_skip
	v_mov_b32_e32 v56, v72
	v_mov_b32_e32 v57, 0
	v_lshl_add_u64 v[56:57], v[56:57], 4, s[54:55]
	v_add_co_u32_e32 v60, vcc, 0x1000, v56
	s_nop 1
	v_addc_co_u32_e32 v61, vcc, 0, v57, vcc
	global_load_dwordx4 v[220:223], v[56:57], off
	global_load_dwordx4 v[224:227], v[56:57], off offset:1024
	global_load_dwordx4 v[228:231], v[56:57], off offset:2048
	global_load_dwordx4 v[232:235], v[56:57], off offset:3072
	global_load_dwordx4 v[236:239], v[60:61], off
	global_load_dwordx4 v[240:243], v[60:61], off offset:1024
	global_load_dwordx4 v[244:247], v[60:61], off offset:2048
	global_load_dwordx4 v[248:251], v[60:61], off offset:3072
	s_waitcnt vmcnt(0)

; __device__ __forceinline__ uint2 pack4(f32x4 v) { uint2 u; u.x = cvt_pk_bf16(v[0], v[1]); u.y = cvt_pk_bf16(v[2], v[3]); return u; }
; #define MFMA16(a, b, c) __builtin_amdgcn_mfma_f32_16x16x32_bf16(a, b, c, 0, 0, 0)
; __device__ __forceinline__ void scan_phase(PREF p, char* smem, const int wid_u) {
;     ...
;       } else if (wave == 2 || wave == 3 || wave >= 6) {
;         const int vtile = wave < 4 ? wave - 2 : wave - 4;
;         const bf16x8 vf = ldfrag(VT, 40, vtile * 16, 0, fr, fq);
;         const f32x4 zero = {0.f, 0.f, 0.f, 0.f};
; #pragma unroll
;         for (int tt = 0; tt < 2; ++tt) {
;           const f32x4 acc = MFMA16(ldfrag(NakT, 40, tt * 16, 0, fr, fq), vf, zero);
;           *(uint2*)(VNb + (vtile * 16 + fr) * 40 + tt * 16 + fq * 4) = pack4(acc);
;         }
.LBB0_556:
	s_andn2_b64 vcc, exec, s[66:67]
	s_cbranch_vccnz .LBB0_558
	s_cmp_gt_u32 s90, 3
	s_cbranch_scc1 .LBB0_558
	v_add_u32_e32 v64, v130, v165
	ds_read_b128 v[56:59], v64 offset:4096
	v_add_u32_e32 v60, v131, v136
	ds_read_b128 v[94:97], v60
	ds_read_b128 v[66:69], v64 offset:5376
	ds_read_b128 v[60:63], v60 offset:2560
	s_waitcnt lgkmcnt(2)
	v_mfma_f32_16x16x32_bf16 v[98:101], v[56:59], v[94:97], 0
	s_waitcnt lgkmcnt(1)
	v_mfma_f32_16x16x32_bf16 v[102:105], v[66:69], v[94:97], 0
	s_waitcnt lgkmcnt(0)
	v_mfma_f32_16x16x32_bf16 v[56:59], v[56:59], v[60:63], 0
	v_mfma_f32_16x16x32_bf16 v[66:69], v[66:69], v[60:63], 0
	s_nop 3
	v_cvt_pk_bf16_f32 v98, v98, v99
	v_cvt_pk_bf16_f32 v99, v100, v101
	ds_write_b64 v173, v[98:99] offset:39936
	v_cvt_pk_bf16_f32 v102, v102, v103
	v_cvt_pk_bf16_f32 v103, v104, v105
	ds_write_b64 v173, v[102:103] offset:39968
	s_nop 3
	v_cvt_pk_bf16_f32 v56, v56, v57
	v_cvt_pk_bf16_f32 v57, v58, v59
	ds_write_b64 v173, v[56:57] offset:42496
	v_cvt_pk_bf16_f32 v66, v66, v67
	v_cvt_pk_bf16_f32 v67, v68, v69
	ds_write_b64 v173, v[66:67] offset:42528

; __device__ __forceinline__ float quad_sum(float x) { x += dpp_f<0xB1>(x); x += dpp_f<0x4E>(x); return x; }
; __device__ __forceinline__ void scan_phase(PREF p, char* smem, const int wid_u) {
;     ...
;           shift16(ra, cst + 2 * 64 + cq * 16, cst + 0 * 64 + cq * 16, v16);
;           float kk[16], ss = 0.f;
; #pragma unroll
;           for (int q = 0; q < 16; ++q) { kk[q] = v16[q] * cst[5 * 64 + cq * 16 + q]; ss += kk[q] * kk[q]; }
;           ss = quad_sum(ss);
;           const float inv = 1.f / fmaxf(sqrtf(ss), 1e-12f);
; #pragma unroll
;           for (int q = 0; q < 4; ++q) {
;             *(f32x4*)(stepbuf + 1 * SV + j * 64 + cq * 16 + q * 4) = (f32x4){v16[q * 4], v16[q * 4 + 1], v16[q * 4 + 2], v16[q * 4 + 3]};
;             *(f32x4*)(stepbuf + 3 * SV + j * 64 + cq * 16 + q * 4) = (f32x4){-kk[q * 4] * inv, -kk[q * 4 + 1] * inv, -kk[q * 4 + 2] * inv, -kk[q * 4 + 3] * inv};
;           }
;           shift16(rb, cst + 4 * 64 + cq * 16, cst + 8 * 64 + cq * 16, v16);
; #pragma unroll
;           for (int q = 0; q < 4; ++q) *(f32x4*)(stepbuf + 5 * SV + j * 64 + cq * 16 + q * 4) = (f32x4){v16[q * 4], v16[q * 4 + 1], v16[q * 4 + 2], v16[q * 4 + 3]};
.LBB0_566:
	s_add_i32 s40, s94, -1
	s_cmp_lt_u32 s40, s44
	s_cselect_b64 s[80:81], -1, 0
	s_cmp_ge_u32 s40, s44
	s_cbranch_scc1 .LBB0_578
	s_mov_b64 s[40:41], -1
	s_and_b64 vcc, exec, s[56:57]
	s_cbranch_vccz .LBB0_573
	s_waitcnt vmcnt(1)
	v_lshlrev_b32_e32 v94, 16, v4
	v_and_b32_e32 v95, 0xffff0000, v4
	v_lshlrev_b32_e32 v96, 16, v0
	v_and_b32_e32 v97, 0xffff0000, v0
	v_lshlrev_b32_e32 v98, 16, v5
	v_and_b32_e32 v99, 0xffff0000, v5
	v_lshlrev_b32_e32 v100, 16, v1
	v_and_b32_e32 v101, 0xffff0000, v1
	v_lshlrev_b32_e32 v102, 16, v6
	v_and_b32_e32 v103, 0xffff0000, v6
	v_lshlrev_b32_e32 v104, 16, v2
	v_and_b32_e32 v105, 0xffff0000, v2
	v_lshlrev_b32_e32 v190, 16, v7
	v_and_b32_e32 v191, 0xffff0000, v7
	v_lshlrev_b32_e32 v192, 16, v3
	v_and_b32_e32 v193, 0xffff0000, v3
	s_waitcnt vmcnt(0)
	v_lshlrev_b32_e32 v194, 16, v8
	v_and_b32_e32 v195, 0xffff0000, v8
	v_lshlrev_b32_e32 v196, 16, v28
	v_and_b32_e32 v197, 0xffff0000, v28
	v_lshlrev_b32_e32 v198, 16, v9
	v_and_b32_e32 v199, 0xffff0000, v9
	v_lshlrev_b32_e32 v200, 16, v29
	v_and_b32_e32 v201, 0xffff0000, v29
	v_lshlrev_b32_e32 v202, 16, v10
	v_and_b32_e32 v203, 0xffff0000, v10
	v_lshlrev_b32_e32 v204, 16, v30
	v_and_b32_e32 v205, 0xffff0000, v30
	v_lshlrev_b32_e32 v206, 16, v11
	v_and_b32_e32 v207, 0xffff0000, v11
	v_lshlrev_b32_e32 v208, 16, v31
	v_and_b32_e32 v209, 0xffff0000, v31
	v_lshlrev_b32_e32 v56, 16, v12
	v_and_b32_e32 v57, 0xffff0000, v12
	v_lshlrev_b32_e32 v58, 16, v13
	v_and_b32_e32 v59, 0xffff0000, v13
	v_lshlrev_b32_e32 v60, 16, v14
	v_and_b32_e32 v61, 0xffff0000, v14
	v_lshlrev_b32_e32 v62, 16, v15
	v_and_b32_e32 v63, 0xffff0000, v15
	v_lshlrev_b32_e32 v64, 16, v16
	v_and_b32_e32 v65, 0xffff0000, v16
	v_lshlrev_b32_e32 v66, 16, v17
	v_and_b32_e32 v67, 0xffff0000, v17
	v_lshlrev_b32_e32 v68, 16, v18
	v_and_b32_e32 v69, 0xffff0000, v18
	v_lshlrev_b32_e32 v70, 16, v19
	v_and_b32_e32 v71, 0xffff0000, v19
	v_pk_add_f32 v[106:107], v[94:95], v[96:97]
	v_pk_add_f32 v[108:109], v[98:99], v[100:101]
	s_and_b64 vcc, exec, s[58:59]
	v_pk_add_f32 v[102:103], v[102:103], v[104:105]
	v_pk_add_f32 v[104:105], v[190:191], v[192:193]
	v_pk_add_f32 v[98:99], v[194:195], v[196:197]
	v_pk_add_f32 v[100:101], v[198:199], v[200:201]
	v_pk_add_f32 v[94:95], v[202:203], v[204:205]
	v_pk_add_f32 v[96:97], v[206:207], v[208:209]
	s_cbranch_vccz .LBB0_570
	ds_read_b128 v[190:193], v137
	ds_read_b128 v[194:197], v137 offset:16
	ds_read_b128 v[198:201], v137 offset:32
	ds_read_b128 v[202:205], v137 offset:48
	ds_read_b128 v[206:209], v138
	ds_read_b128 v[210:213], v138 offset:16
	ds_read_b128 v[214:217], v138 offset:32
	ds_read_b128 v[218:221], v138 offset:48
	s_mov_b32 s40, 0xf800000
	s_waitcnt lgkmcnt(3)
	v_pk_mul_f32 v[206:207], v[106:107], v[206:207]
	s_nop 0
	v_pk_fma_f32 v[190:191], v[190:191], v[56:57], v[206:207]
	v_pk_mul_f32 v[206:207], v[108:109], v[208:209]
	s_nop 0
	v_pk_fma_f32 v[192:193], v[192:193], v[58:59], v[206:207]
	s_waitcnt lgkmcnt(2)
	v_pk_mul_f32 v[206:207], v[102:103], v[210:211]
	ds_write_b128 v139, v[190:193]
	v_pk_fma_f32 v[194:195], v[194:195], v[60:61], v[206:207]
	v_pk_mul_f32 v[206:207], v[104:105], v[212:213]
	s_nop 0
	v_pk_fma_f32 v[196:197], v[196:197], v[62:63], v[206:207]
	s_waitcnt lgkmcnt(2)
	v_pk_mul_f32 v[206:207], v[98:99], v[214:215]
	ds_write_b128 v139, v[194:197] offset:16
	v_pk_fma_f32 v[198:199], v[198:199], v[64:65], v[206:207]
	v_pk_mul_f32 v[206:207], v[100:101], v[216:217]
	s_nop 0
	v_pk_fma_f32 v[200:201], v[200:201], v[66:67], v[206:207]
	ds_read_b128 v[206:209], v138 offset:1312
	ds_write_b128 v139, v[198:201] offset:32
	s_waitcnt lgkmcnt(1)
	v_pk_mul_f32 v[212:213], v[200:201], v[208:209]
	v_pk_mul_f32 v[208:209], v[94:95], v[218:219]
	v_pk_mul_f32 v[198:199], v[198:199], v[206:207]
	v_pk_fma_f32 v[202:203], v[202:203], v[68:69], v[208:209]
	ds_read_b128 v[208:211], v138 offset:1328
	v_pk_mul_f32 v[200:201], v[198:199], v[198:199]
	v_pk_mul_f32 v[214:215], v[212:213], v[212:213]
	v_lshlrev_b32_e32 v206, 16, v36
	v_and_b32_e32 v207, 0xffff0000, v36
	s_waitcnt lgkmcnt(0)
	v_pk_mul_f32 v[216:217], v[202:203], v[208:209]
	v_pk_mul_f32 v[208:209], v[96:97], v[220:221]
	v_pk_mul_f32 v[218:219], v[216:217], v[216:217]
	v_pk_fma_f32 v[204:205], v[204:205], v[70:71], v[208:209]
	s_nop 0
	v_pk_mul_f32 v[220:221], v[204:205], v[210:211]
	ds_read_b128 v[208:211], v138 offset:1280
	v_pk_mul_f32 v[222:223], v[220:221], v[220:221]
	s_waitcnt lgkmcnt(0)
	v_pk_mul_f32 v[208:209], v[190:191], v[208:209]
	v_pk_mul_f32 v[210:211], v[192:193], v[210:211]
	ds_read_b128 v[190:193], v138 offset:1296
	v_pk_mul_f32 v[224:225], v[208:209], v[208:209]
	v_pk_mul_f32 v[226:227], v[210:211], v[210:211]
	s_waitcnt lgkmcnt(0)
; __device__ __forceinline__ float quad_sum(float x) { x += dpp_f<0xB1>(x); x += dpp_f<0x4E>(x); return x; }
; __device__ __forceinline__ void scan_phase(PREF p, char* smem, const int wid_u) {
;     ...
;           float kk[16], ss = 0.f;
; #pragma unroll
;           for (int q = 0; q < 16; ++q) { kk[q] = v16[q] * cst[5 * 64 + cq * 16 + q]; ss += kk[q] * kk[q]; }
;           ss = quad_sum(ss);
;           const float inv = 1.f / fmaxf(sqrtf(ss), 1e-12f);
; #pragma unroll
;           for (int q = 0; q < 4; ++q) {
;             *(f32x4*)(stepbuf + 1 * SV + j * 64 + cq * 16 + q * 4) = (f32x4){v16[q * 4], v16[q * 4 + 1], v16[q * 4 + 2], v16[q * 4 + 3]};
;             *(f32x4*)(stepbuf + 3 * SV + j * 64 + cq * 16 + q * 4) = (f32x4){-kk[q * 4] * inv, -kk[q * 4 + 1] * inv, -kk[q * 4 + 2] * inv, -kk[q * 4 + 3] * inv};
;           }
;           shift16(rb, cst + 4 * 64 + cq * 16, cst + 8 * 64 + cq * 16, v16);
; #pragma unroll
;           for (int q = 0; q < 4; ++q) *(f32x4*)(stepbuf + 5 * SV + j * 64 + cq * 16 + q * 4) = (f32x4){v16[q * 4], v16[q * 4 + 1], v16[q * 4 + 2], v16[q * 4 + 3]};
	v_pk_mul_f32 v[194:195], v[194:195], v[190:191]
	v_pk_mul_f32 v[196:197], v[196:197], v[192:193]
	v_pk_add_f32 v[224:225], v[224:225], v[226:227]
	v_pk_add_f32 v[200:201], v[200:201], v[214:215]
	v_pk_mul_f32 v[190:191], v[194:195], v[194:195]
	v_pk_mul_f32 v[192:193], v[196:197], v[196:197]
	v_pk_add_f32 v[218:219], v[218:219], v[222:223]
	v_pk_add_f32 v[190:191], v[190:191], v[192:193]
	v_pk_add_f32 v[200:201], v[200:201], v[218:219]
	v_pk_add_f32 v[224:225], v[224:225], v[190:191]
	s_mov_b64 s[40:41], 0
	v_pk_add_f32 v[224:225], v[224:225], v[200:201]
	s_nop 0
	v_add_f32_e32 v78, v224, v225
	v_lshlrev_b32_e32 v222, 16, v24
	v_and_b32_e32 v223, 0xffff0000, v24
	v_add_f32_dpp v78, v78, v78 quad_perm:[1,0,3,2] row_mask:0xf bank_mask:0xf bound_ctrl:1
	s_nop 1
	v_add_f32_dpp v78, v78, v78 quad_perm:[2,3,0,1] row_mask:0xf bank_mask:0xf bound_ctrl:1
	s_nop 0
	v_rsq_f32_e32 v78, v78
	s_nop 0
	v_min_f32_e32 v78, 0x5368d4a5, v78
	v_pk_mul_f32 v[192:193], v[78:79], v[210:211] op_sel_hi:[0,1] neg_lo:[0,1] neg_hi:[0,1]
	v_pk_mul_f32 v[190:191], v[78:79], v[208:209] op_sel_hi:[0,1] neg_lo:[0,1] neg_hi:[0,1]
	ds_write_b128 v140, v[190:193]
	v_pk_mul_f32 v[192:193], v[78:79], v[196:197] op_sel_hi:[0,1] neg_lo:[0,1] neg_hi:[0,1]
	v_pk_mul_f32 v[190:191], v[78:79], v[194:195] op_sel_hi:[0,1] neg_lo:[0,1] neg_hi:[0,1]
	ds_write_b128 v140, v[190:193] offset:16
	v_pk_mul_f32 v[192:193], v[78:79], v[212:213] op_sel_hi:[0,1] neg_lo:[0,1] neg_hi:[0,1]
	v_pk_mul_f32 v[190:191], v[78:79], v[198:199] op_sel_hi:[0,1] neg_lo:[0,1] neg_hi:[0,1]
	ds_write_b128 v140, v[190:193] offset:32
	ds_write_b128 v139, v[202:205] offset:48
	v_pk_mul_f32 v[192:193], v[78:79], v[220:221] op_sel_hi:[0,1] neg_lo:[0,1] neg_hi:[0,1]
	v_pk_mul_f32 v[190:191], v[78:79], v[216:217] op_sel_hi:[0,1] neg_lo:[0,1] neg_hi:[0,1]
	ds_write_b128 v140, v[190:193] offset:48
	v_lshlrev_b32_e32 v208, 16, v32
	v_and_b32_e32 v209, 0xffff0000, v32
	ds_read_b128 v[190:193], v141
	ds_read_b128 v[194:197], v141 offset:16
	ds_read_b128 v[198:201], v141 offset:32
	ds_read_b128 v[202:205], v141 offset:48
	v_pk_add_f32 v[224:225], v[206:207], v[208:209]
	ds_read_b128 v[206:209], v142
	ds_read_b128 v[210:213], v142 offset:16
	ds_read_b128 v[214:217], v142 offset:32
	ds_read_b128 v[218:221], v142 offset:48
	s_waitcnt lgkmcnt(3)
	v_pk_mul_f32 v[206:207], v[224:225], v[206:207]
	s_nop 0
	v_pk_fma_f32 v[190:191], v[190:191], v[222:223], v[206:207]
	v_lshlrev_b32_e32 v222, 16, v37
	v_and_b32_e32 v223, 0xffff0000, v37
	v_lshlrev_b32_e32 v224, 16, v33
	v_and_b32_e32 v225, 0xffff0000, v33
	v_pk_add_f32 v[222:223], v[222:223], v[224:225]
	v_lshlrev_b32_e32 v206, 16, v25
	v_and_b32_e32 v207, 0xffff0000, v25
	v_pk_mul_f32 v[208:209], v[222:223], v[208:209]
	v_lshlrev_b32_e32 v222, 16, v34
	v_pk_fma_f32 v[192:193], v[192:193], v[206:207], v[208:209]
	v_lshlrev_b32_e32 v208, 16, v38
	v_and_b32_e32 v209, 0xffff0000, v38
	v_and_b32_e32 v223, 0xffff0000, v34
	v_pk_add_f32 v[208:209], v[208:209], v[222:223]
	v_lshlrev_b32_e32 v206, 16, v26
	v_and_b32_e32 v207, 0xffff0000, v26
	s_waitcnt lgkmcnt(2)
	v_pk_mul_f32 v[208:209], v[208:209], v[210:211]
	v_lshlrev_b32_e32 v210, 16, v35
	v_pk_fma_f32 v[194:195], v[194:195], v[206:207], v[208:209]
	v_lshlrev_b32_e32 v208, 16, v39
	v_and_b32_e32 v209, 0xffff0000, v39
	v_and_b32_e32 v211, 0xffff0000, v35
	v_pk_add_f32 v[208:209], v[208:209], v[210:211]
	v_lshlrev_b32_e32 v206, 16, v27
	v_and_b32_e32 v207, 0xffff0000, v27
	v_pk_mul_f32 v[208:209], v[208:209], v[212:213]
	v_lshlrev_b32_e32 v210, 16, v44
	v_pk_fma_f32 v[196:197], v[196:197], v[206:207], v[208:209]
	v_lshlrev_b32_e32 v208, 16, v40
	v_and_b32_e32 v209, 0xffff0000, v40
	v_and_b32_e32 v211, 0xffff0000, v44
	v_pk_add_f32 v[208:209], v[208:209], v[210:211]
	v_lshlrev_b32_e32 v206, 16, v20
	v_and_b32_e32 v207, 0xffff0000, v20
	s_waitcnt lgkmcnt(1)
	v_pk_mul_f32 v[208:209], v[208:209], v[214:215]
	v_lshlrev_b32_e32 v210, 16, v45
	v_pk_fma_f32 v[198:199], v[198:199], v[206:207], v[208:209]
	v_lshlrev_b32_e32 v208, 16, v41
	v_and_b32_e32 v209, 0xffff0000, v41
	v_and_b32_e32 v211, 0xffff0000, v45
	v_pk_add_f32 v[208:209], v[208:209], v[210:211]
	v_lshlrev_b32_e32 v206, 16, v21
	v_and_b32_e32 v207, 0xffff0000, v21
	v_pk_mul_f32 v[208:209], v[208:209], v[216:217]
	v_lshlrev_b32_e32 v210, 16, v46
	v_pk_fma_f32 v[200:201], v[200:201], v[206:207], v[208:209]
	v_lshlrev_b32_e32 v208, 16, v42
	v_and_b32_e32 v209, 0xffff0000, v42
	v_and_b32_e32 v211, 0xffff0000, v46
	v_pk_add_f32 v[208:209], v[208:209], v[210:211]
	v_lshlrev_b32_e32 v206, 16, v22
	v_and_b32_e32 v207, 0xffff0000, v22
	s_waitcnt lgkmcnt(0)
	v_pk_mul_f32 v[208:209], v[208:209], v[218:219]
	v_lshlrev_b32_e32 v210, 16, v47
	v_pk_fma_f32 v[202:203], v[202:203], v[206:207], v[208:209]
	v_lshlrev_b32_e32 v208, 16, v43
	v_and_b32_e32 v209, 0xffff0000, v43
	v_and_b32_e32 v211, 0xffff0000, v47
	v_pk_add_f32 v[208:209], v[208:209], v[210:211]
	v_lshlrev_b32_e32 v206, 16, v23
	v_and_b32_e32 v207, 0xffff0000, v23
	v_pk_mul_f32 v[208:209], v[208:209], v[220:221]
	s_nop 0
	v_pk_fma_f32 v[204:205], v[204:205], v[206:207], v[208:209]
	ds_write_b128 v177, v[190:193]
	ds_write_b128 v177, v[194:197] offset:16
	ds_write_b128 v177, v[198:201] offset:32
	ds_write_b128 v177, v[202:205] offset:48

; __device__ __forceinline__ void scan_phase(PREF p, char* smem, const int wid_u) {
;     ...
;       if (c + 2 < nch) {
;         const int is2 = (c + 2) * 32 + th * 16 + tl;
;         const int t2 = d ? T - 1 - is2 : is2;
;         const int row2 = r0seq + t2;
;         if (role >= 2) load_raw16(ra, z, row2, t2, T, colA);
;         if (role == 3) load_raw16(rb, z, row2, t2, T, colB);
.LBB0_592:
	v_mad_u64_u32 v[0:1], s[82:83], v59, s88, v[74:75]
	v_mov_b32_e32 v1, v79
	v_lshl_add_u64 v[56:57], v[0:1], 1, s[50:51]
	global_load_dwordx4 v[16:19], v[56:57], off offset:16
	global_load_dwordx4 v[12:15], v[56:57], off
	s_add_i32 s82, s94, 1
	s_cmp_eq_u32 s82, s44
	s_cbranch_scc1 .Lpf_slow_a
	v_lshl_add_u64 v[8:9], v[56:57], 0, s[76:77]
	v_lshl_add_u64 v[28:29], v[56:57], 0, s[78:79]
	global_load_dwordx4 v[4:7], v[8:9], off
	s_nop 0
	global_load_dwordx4 v[8:11], v[8:9], off offset:16
	global_load_dwordx4 v[0:3], v[28:29], off
	s_nop 0
	global_load_dwordx4 v[28:31], v[28:29], off offset:16

; __device__ __forceinline__ void scan_phase(PREF p, char* smem, const int wid_u) {
;     ...
;       if (c + 2 < nch) {
;         const int is2 = (c + 2) * 32 + th * 16 + tl;
;         const int t2 = d ? T - 1 - is2 : is2;
;         const int row2 = r0seq + t2;
;         if (role >= 2) load_raw16(ra, z, row2, t2, T, colA);
;         if (role == 3) load_raw16(rb, z, row2, t2, T, colB);
.LBB0_597:
	v_mad_u64_u32 v[20:21], s[40:41], v59, s88, v[76:77]
	v_mov_b32_e32 v21, v79
	v_lshl_add_u64 v[56:57], v[20:21], 1, s[50:51]
	global_load_dwordx4 v[20:23], v[56:57], off offset:16
	global_load_dwordx4 v[24:27], v[56:57], off
	s_add_i32 s40, s94, 1
	s_cmp_eq_u32 s40, s44
	s_cbranch_scc1 .Lpf_slow_b
	v_lshl_add_u64 v[40:41], v[56:57], 0, s[76:77]
	v_lshl_add_u64 v[44:45], v[56:57], 0, s[78:79]
	global_load_dwordx4 v[36:39], v[40:41], off
	s_nop 0
	global_load_dwordx4 v[40:43], v[40:41], off offset:16
	global_load_dwordx4 v[32:35], v[44:45], off
	s_nop 0
	global_load_dwordx4 v[44:47], v[44:45], off offset:16
